# GEMM tile prologue: accumulator zeroing hoisted above the wait for the first K-stages
# speedup vs baseline: 1.0152x; 1.0152x over previous
.LBB0_33:
	s_or_b64 exec, exec, s[52:53]
	v_mov_b32_e32 v3, v1
	v_lshl_add_u64 v[12:13], s[0:1], 0, v[2:3]
	s_waitcnt vmcnt(8)
	v_lshl_add_u64 v[16:17], s[14:15], 0, v[2:3]
	v_lshl_add_u64 v[20:21], s[16:17], 0, v[2:3]
	v_lshl_add_u64 v[130:131], s[72:73], 0, v[2:3]
	v_and_b32_e32 v146, 15, v142
	v_bfe_u32 v145, v142, 4, 2
	v_lshlrev_b32_e32 v3, 2, v142
	v_add_u32_e32 v156, 0x18000, v147
	v_lshl_add_u64 v[10:11], s[0:1], 0, v[0:1]
	v_lshl_add_u64 v[14:15], s[14:15], 0, v[0:1]
	v_lshl_add_u64 v[18:19], s[16:17], 0, v[0:1]
	v_lshl_add_u64 v[132:133], s[72:73], 0, v[0:1]
	v_lshlrev_b32_e32 v0, 6, v146
	v_lshlrev_b32_e32 v2, 4, v145
	v_and_b32_e32 v3, 32, v3
	s_mov_b64 s[14:15], 0x80
	v_readfirstlane_b32 s0, v156
	v_add_u32_e32 v157, 0x1a000, v147
	v_bitop3_b32 v22, v2, v3, v0 bitop3:0x36
	v_lshl_add_u64 v[2:3], v[10:11], 0, s[14:15]
	s_mov_b32 m0, s0
	v_readfirstlane_b32 s0, v157
	v_add_u32_e32 v158, 0x8000, v147
	s_waitcnt vmcnt(4)
	s_barrier
	global_load_lds_dwordx4 v[2:3], off
	v_lshl_add_u64 v[2:3], v[12:13], 0, s[14:15]
	s_mov_b32 m0, s0
	v_readfirstlane_b32 s0, v158
	v_add_u32_e32 v159, 0xa000, v147
	global_load_lds_dwordx4 v[2:3], off
	v_lshl_add_u64 v[2:3], v[14:15], 0, s[14:15]
	s_mov_b32 m0, s0
	v_readfirstlane_b32 s0, v159
	v_add_u32_e32 v160, 0x1c000, v147
	global_load_lds_dwordx4 v[2:3], off
	v_lshl_add_u64 v[2:3], v[16:17], 0, s[14:15]
	s_mov_b32 m0, s0
	v_readfirstlane_b32 s0, v160
	v_add_u32_e32 v161, 0x1e000, v147
	global_load_lds_dwordx4 v[2:3], off
	v_lshl_add_u64 v[2:3], v[18:19], 0, s[14:15]
	s_mov_b32 m0, s0
	v_readfirstlane_b32 s0, v161
	global_load_lds_dwordx4 v[2:3], off
	v_lshl_add_u64 v[2:3], v[20:21], 0, s[14:15]
	s_mov_b32 m0, s0
	s_sub_i32 s1, s56, s63
	global_load_lds_dwordx4 v[2:3], off
	s_sub_i32 s1, s1, s62
	v_lshlrev_b32_e32 v0, 15, v4
	s_sext_i32_i16 s1, s1
	v_and_b32_e32 v0, 0xffff0000, v0
	s_lshl_b32 s0, s57, 10
	s_lshl_b32 s1, s1, 8
	v_lshl_add_u32 v0, v5, 12, v0
	v_and_b32_e32 v2, 1, v4
	s_add_i32 s0, s0, s1
	v_lshl_or_b32 v0, v2, 6, v0
	v_lshlrev_b32_e32 v2, 15, v6
	s_ashr_i32 s1, s0, 31
	v_and_b32_e32 v2, 0xffff0000, v2
	s_lshl_b64 s[0:1], s[0:1], 12
	v_lshl_add_u32 v2, v8, 12, v2
	v_and_b32_e32 v3, 1, v6
	s_add_u32 s0, s6, s0
	v_lshl_or_b32 v2, v3, 6, v2
	v_lshl_add_u32 v0, v7, 1, v0
	s_addc_u32 s1, s7, s1
	v_lshl_add_u32 v2, v9, 1, v2
	v_mov_b32_e32 v3, v1
	v_lshl_add_u64 v[134:135], s[0:1], 0, v[0:1]
	v_lshl_add_u64 v[136:137], s[0:1], 0, v[2:3]
	s_add_u32 s0, s88, s12
	v_bfe_u32 v144, v142, 6, 2
	v_mov_b32_e32 v4, 0
	v_mov_b32_e32 v5, 0
	v_mov_b32_e32 v6, 0
	v_mov_b32_e32 v7, 0
	v_mov_b32_e32 v8, 0
	v_mov_b32_e32 v9, 0
	v_mov_b32_e32 v10, 0
	v_mov_b32_e32 v11, 0
	v_mov_b32_e32 v12, 0
	v_mov_b32_e32 v13, 0
	v_mov_b32_e32 v14, 0
	v_mov_b32_e32 v15, 0
	v_mov_b32_e32 v16, 0
	v_mov_b32_e32 v17, 0
	v_mov_b32_e32 v18, 0
	v_mov_b32_e32 v19, 0
	v_mov_b32_e32 v20, 0
	v_mov_b32_e32 v21, 0
	v_mov_b32_e32 v25, 0
	v_mov_b32_e32 v26, 0
	v_mov_b32_e32 v27, 0
	v_mov_b32_e32 v28, 0
	v_mov_b32_e32 v29, 0
	v_mov_b32_e32 v30, 0
	v_mov_b32_e32 v31, 0
	v_mov_b32_e32 v32, 0
	v_mov_b32_e32 v33, 0
	v_mov_b32_e32 v34, 0
	v_mov_b32_e32 v35, 0
	v_mov_b32_e32 v36, 0
	v_mov_b32_e32 v37, 0
	v_mov_b32_e32 v38, 0
	v_mov_b32_e32 v39, 0
	v_mov_b32_e32 v40, 0
	v_mov_b32_e32 v41, 0
	v_mov_b32_e32 v42, 0
	v_mov_b32_e32 v43, 0
	v_mov_b32_e32 v44, 0
	v_mov_b32_e32 v45, 0
	v_mov_b32_e32 v46, 0
	v_mov_b32_e32 v47, 0
	v_mov_b32_e32 v48, 0
	v_mov_b32_e32 v49, 0
	v_mov_b32_e32 v50, 0
	v_mov_b32_e32 v51, 0
	v_mov_b32_e32 v52, 0
	v_mov_b32_e32 v53, 0
	v_mov_b32_e32 v54, 0
	v_mov_b32_e32 v55, 0
	v_mov_b32_e32 v56, 0
	v_mov_b32_e32 v57, 0
	v_mov_b32_e32 v58, 0
	v_mov_b32_e32 v59, 0
	v_mov_b32_e32 v60, 0
	v_mov_b32_e32 v61, 0
	v_mov_b32_e32 v62, 0
	v_mov_b32_e32 v63, 0
	v_mov_b32_e32 v64, 0
	v_mov_b32_e32 v65, 0
	v_mov_b32_e32 v70, 0
	v_mov_b32_e32 v71, 0
	v_mov_b32_e32 v72, 0
	v_mov_b32_e32 v73, 0
	v_mov_b32_e32 v86, 0
	v_mov_b32_e32 v87, 0
	v_mov_b32_e32 v88, 0
	v_mov_b32_e32 v89, 0
	v_mov_b32_e32 v90, 0
	v_mov_b32_e32 v91, 0
	v_mov_b32_e32 v92, 0
	v_mov_b32_e32 v93, 0
	v_mov_b32_e32 v94, 0
	v_mov_b32_e32 v95, 0
	v_mov_b32_e32 v96, 0
	v_mov_b32_e32 v97, 0
	v_mov_b32_e32 v98, 0
	v_mov_b32_e32 v99, 0
	v_mov_b32_e32 v100, 0
	v_mov_b32_e32 v101, 0
	v_mov_b32_e32 v102, 0
	v_mov_b32_e32 v103, 0
	v_mov_b32_e32 v104, 0
	v_mov_b32_e32 v105, 0
	v_mov_b32_e32 v106, 0
	v_mov_b32_e32 v107, 0
	v_mov_b32_e32 v108, 0
	v_mov_b32_e32 v109, 0
	v_mov_b32_e32 v110, 0
	v_mov_b32_e32 v111, 0
	v_mov_b32_e32 v112, 0
	v_mov_b32_e32 v113, 0
	v_mov_b32_e32 v114, 0
	v_mov_b32_e32 v115, 0
	v_mov_b32_e32 v116, 0
	v_mov_b32_e32 v117, 0
	v_mov_b32_e32 v118, 0
	v_mov_b32_e32 v119, 0
	v_mov_b32_e32 v120, 0
	v_mov_b32_e32 v121, 0
	v_mov_b32_e32 v122, 0
	v_mov_b32_e32 v123, 0
	v_mov_b32_e32 v124, 0
	v_mov_b32_e32 v125, 0
	v_mov_b32_e32 v126, 0
	v_mov_b32_e32 v127, 0
	v_mov_b32_e32 v128, 0
	v_mov_b32_e32 v129, 0
	v_mov_b32_e32 v66, 0
	v_mov_b32_e32 v67, 0
	v_mov_b32_e32 v68, 0
	v_mov_b32_e32 v69, 0
	v_mov_b32_e32 v74, 0
	v_mov_b32_e32 v75, 0
	v_mov_b32_e32 v76, 0
	v_mov_b32_e32 v77, 0
	v_mov_b32_e32 v78, 0
	v_mov_b32_e32 v79, 0
	v_mov_b32_e32 v80, 0
	v_mov_b32_e32 v81, 0
	v_mov_b32_e32 v82, 0
	v_mov_b32_e32 v83, 0
	v_mov_b32_e32 v84, 0
	v_mov_b32_e32 v85, 0
	s_waitcnt vmcnt(6)
	s_addc_u32 s1, s89, s13
	v_lshlrev_b32_e32 v23, 13, v143
	v_lshl_or_b32 v24, v144, 12, v212
	v_lshl_add_u64 v[140:141], s[0:1], 0, v[2:3]
	v_mov_b32_e32 v2, 0
	v_lshl_add_u64 v[138:139], s[0:1], 0, v[0:1]
	s_mov_b32 s0, -2
	s_mov_b64 s[12:13], 0
	v_add_u32_e32 v151, v24, v22
	v_add_u32_e32 v0, v23, v22
	v_mov_b32_e32 v3, v2
	v_mov_b32_e32 v22, v2
	v_mov_b32_e32 v23, v2
	v_mov_b32_e32 v24, v2
	s_barrier
	v_add_u32_e32 v162, 0xc000, v147
	v_add_u32_e32 v163, 0xe000, v147
	v_readfirstlane_b32 s1, v147
	s_nop 1

.LBB0_84:
	s_or_b64 exec, exec, s[52:53]
	v_mov_b32_e32 v3, v1
	v_lshl_add_u64 v[12:13], s[0:1], 0, v[2:3]
	v_lshl_add_u64 v[16:17], s[12:13], 0, v[2:3]
	v_lshl_add_u64 v[20:21], s[14:15], 0, v[2:3]
	v_lshl_add_u64 v[130:131], s[16:17], 0, v[2:3]
	v_and_b32_e32 v146, 15, v142
	v_bfe_u32 v145, v142, 4, 2
	v_lshlrev_b32_e32 v3, 2, v142
	v_add_u32_e32 v156, 0x18000, v147
	v_lshl_add_u64 v[10:11], s[0:1], 0, v[0:1]
	v_lshl_add_u64 v[14:15], s[12:13], 0, v[0:1]
	v_lshl_add_u64 v[18:19], s[14:15], 0, v[0:1]
	v_lshl_add_u64 v[132:133], s[16:17], 0, v[0:1]
	v_lshlrev_b32_e32 v0, 6, v146
	v_lshlrev_b32_e32 v2, 4, v145
	v_and_b32_e32 v3, 32, v3
	s_mov_b64 s[12:13], 0x80
	v_readfirstlane_b32 s0, v156
	v_add_u32_e32 v157, 0x1a000, v147
	v_bitop3_b32 v22, v2, v3, v0 bitop3:0x36
	v_lshl_add_u64 v[2:3], v[10:11], 0, s[12:13]
	s_mov_b32 m0, s0
	v_readfirstlane_b32 s0, v157
	v_add_u32_e32 v158, 0x8000, v147
	s_waitcnt vmcnt(4)
	s_barrier
	global_load_lds_dwordx4 v[2:3], off
	v_lshl_add_u64 v[2:3], v[12:13], 0, s[12:13]
	s_mov_b32 m0, s0
	v_readfirstlane_b32 s0, v158
	v_add_u32_e32 v159, 0xa000, v147
	global_load_lds_dwordx4 v[2:3], off
	v_lshl_add_u64 v[2:3], v[14:15], 0, s[12:13]
	s_mov_b32 m0, s0
	v_readfirstlane_b32 s0, v159
	v_add_u32_e32 v160, 0x1c000, v147
	global_load_lds_dwordx4 v[2:3], off
	v_lshl_add_u64 v[2:3], v[16:17], 0, s[12:13]
	s_mov_b32 m0, s0
	v_readfirstlane_b32 s0, v160
	v_add_u32_e32 v161, 0x1e000, v147
	global_load_lds_dwordx4 v[2:3], off
	v_lshl_add_u64 v[2:3], v[18:19], 0, s[12:13]
	s_mov_b32 m0, s0
	v_readfirstlane_b32 s0, v161
	global_load_lds_dwordx4 v[2:3], off
	v_lshl_add_u64 v[2:3], v[20:21], 0, s[12:13]
	s_mov_b32 m0, s0
	s_sub_i32 s1, s57, s64
	global_load_lds_dwordx4 v[2:3], off
	s_sub_i32 s1, s1, s63
	v_lshlrev_b32_e32 v0, 15, v4
	s_sext_i32_i16 s1, s1
	v_and_b32_e32 v0, 0xffff0000, v0
	s_lshl_b32 s0, s62, 10
	s_lshl_b32 s1, s1, 8
	v_lshl_add_u32 v0, v5, 12, v0
	v_and_b32_e32 v2, 1, v4
	s_add_i32 s0, s0, s1
	v_lshl_or_b32 v0, v2, 6, v0
	v_lshlrev_b32_e32 v2, 15, v6
	s_ashr_i32 s1, s0, 31
	v_and_b32_e32 v2, 0xffff0000, v2
	s_lshl_b64 s[0:1], s[0:1], 12
	v_lshl_add_u32 v2, v8, 12, v2
	v_and_b32_e32 v3, 1, v6
	s_add_u32 s0, s4, s0
	v_lshl_or_b32 v2, v3, 6, v2
	v_lshl_add_u32 v0, v7, 1, v0
	s_addc_u32 s1, s5, s1
	v_lshl_add_u32 v2, v9, 1, v2
	v_mov_b32_e32 v3, v1
	v_mov_b32_e32 v4, 0
	v_mov_b32_e32 v5, 0
	v_mov_b32_e32 v6, 0
	v_mov_b32_e32 v7, 0
	v_mov_b32_e32 v8, 0
	v_mov_b32_e32 v9, 0
	v_mov_b32_e32 v10, 0
	v_mov_b32_e32 v11, 0
	v_mov_b32_e32 v12, 0
	v_mov_b32_e32 v13, 0
	v_mov_b32_e32 v14, 0
	v_mov_b32_e32 v15, 0
	v_mov_b32_e32 v16, 0
	v_mov_b32_e32 v17, 0
	v_mov_b32_e32 v18, 0
	v_mov_b32_e32 v19, 0
	v_mov_b32_e32 v20, 0
	v_mov_b32_e32 v21, 0
	v_mov_b32_e32 v25, 0
	v_mov_b32_e32 v26, 0
	v_mov_b32_e32 v27, 0
	v_mov_b32_e32 v28, 0
	v_mov_b32_e32 v29, 0
	v_mov_b32_e32 v30, 0
	v_mov_b32_e32 v31, 0
	v_mov_b32_e32 v32, 0
	v_mov_b32_e32 v33, 0
	v_mov_b32_e32 v34, 0
	v_mov_b32_e32 v35, 0
	v_mov_b32_e32 v36, 0
	v_mov_b32_e32 v37, 0
	v_mov_b32_e32 v38, 0
	v_mov_b32_e32 v39, 0
	v_mov_b32_e32 v40, 0
	v_mov_b32_e32 v41, 0
	v_mov_b32_e32 v42, 0
	v_mov_b32_e32 v43, 0
	v_mov_b32_e32 v44, 0
	v_mov_b32_e32 v45, 0
	v_mov_b32_e32 v46, 0
	v_mov_b32_e32 v47, 0
	v_mov_b32_e32 v48, 0
	v_mov_b32_e32 v49, 0
	v_mov_b32_e32 v50, 0
	v_mov_b32_e32 v51, 0
	v_mov_b32_e32 v52, 0
	v_mov_b32_e32 v53, 0
	v_mov_b32_e32 v54, 0
	v_mov_b32_e32 v55, 0
	v_mov_b32_e32 v56, 0
	v_mov_b32_e32 v57, 0
	v_mov_b32_e32 v58, 0
	v_mov_b32_e32 v59, 0
	v_mov_b32_e32 v60, 0
	v_mov_b32_e32 v61, 0
	v_mov_b32_e32 v62, 0
	v_mov_b32_e32 v63, 0
	v_mov_b32_e32 v64, 0
	v_mov_b32_e32 v65, 0
	v_mov_b32_e32 v66, 0
	v_mov_b32_e32 v67, 0
	v_mov_b32_e32 v68, 0
	v_mov_b32_e32 v69, 0
	v_mov_b32_e32 v70, 0
	v_mov_b32_e32 v71, 0
	v_mov_b32_e32 v72, 0
	v_mov_b32_e32 v73, 0
	v_mov_b32_e32 v74, 0
	v_mov_b32_e32 v75, 0
	v_mov_b32_e32 v76, 0
	v_mov_b32_e32 v77, 0
	v_mov_b32_e32 v78, 0
	v_mov_b32_e32 v79, 0
	v_mov_b32_e32 v80, 0
	v_mov_b32_e32 v81, 0
	v_mov_b32_e32 v82, 0
	v_mov_b32_e32 v83, 0
	v_mov_b32_e32 v84, 0
	v_mov_b32_e32 v85, 0
	v_mov_b32_e32 v86, 0
	v_mov_b32_e32 v87, 0
	v_mov_b32_e32 v88, 0
	v_mov_b32_e32 v89, 0
	v_mov_b32_e32 v90, 0
	v_mov_b32_e32 v91, 0
	v_mov_b32_e32 v92, 0
	v_mov_b32_e32 v93, 0
	v_mov_b32_e32 v94, 0
	v_mov_b32_e32 v95, 0
	v_mov_b32_e32 v96, 0
	v_mov_b32_e32 v97, 0
	v_mov_b32_e32 v98, 0
	v_mov_b32_e32 v99, 0
	v_mov_b32_e32 v100, 0
	v_mov_b32_e32 v101, 0
	v_mov_b32_e32 v102, 0
	v_mov_b32_e32 v103, 0
	v_mov_b32_e32 v104, 0
	v_mov_b32_e32 v105, 0
	v_mov_b32_e32 v106, 0
	v_mov_b32_e32 v107, 0
	v_mov_b32_e32 v108, 0
	v_mov_b32_e32 v109, 0
	v_mov_b32_e32 v110, 0
	v_mov_b32_e32 v111, 0
	v_mov_b32_e32 v112, 0
	v_mov_b32_e32 v113, 0
	v_mov_b32_e32 v114, 0
	v_mov_b32_e32 v115, 0
	v_mov_b32_e32 v116, 0
	v_mov_b32_e32 v117, 0
	v_mov_b32_e32 v118, 0
	v_mov_b32_e32 v119, 0
	v_mov_b32_e32 v120, 0
	v_mov_b32_e32 v121, 0
	v_mov_b32_e32 v122, 0
	v_mov_b32_e32 v123, 0
	v_mov_b32_e32 v124, 0
	v_mov_b32_e32 v125, 0
	v_mov_b32_e32 v126, 0
	v_mov_b32_e32 v127, 0
	v_mov_b32_e32 v128, 0
	v_mov_b32_e32 v129, 0
	s_waitcnt vmcnt(6)
	v_lshl_add_u64 v[134:135], s[0:1], 0, v[0:1]
	v_lshl_add_u64 v[136:137], s[0:1], 0, v[2:3]
	s_add_u32 s0, s88, s10
	v_bfe_u32 v144, v142, 6, 2
	s_addc_u32 s1, s89, s11
	v_lshlrev_b32_e32 v23, 13, v143
	v_lshl_or_b32 v24, v144, 12, v212
	v_lshl_add_u64 v[140:141], s[0:1], 0, v[2:3]
	v_mov_b32_e32 v2, 0
	s_barrier
	v_lshl_add_u64 v[138:139], s[0:1], 0, v[0:1]
	s_mov_b32 s0, -2
	s_mov_b64 s[10:11], 0
	v_add_u32_e32 v151, v24, v22
	v_add_u32_e32 v0, v23, v22
	v_mov_b32_e32 v3, v2
	v_mov_b32_e32 v22, v2
	v_mov_b32_e32 v23, v2
	v_mov_b32_e32 v24, v2
	v_add_u32_e32 v162, 0xc000, v147
	v_add_u32_e32 v163, 0xe000, v147
	v_readfirstlane_b32 s1, v147
	s_nop 1

.LBB0_107:
	s_or_b64 exec, exec, s[72:73]
	v_mov_b32_e32 v3, v1
	s_waitcnt vmcnt(8)
	v_lshl_add_u64 v[14:15], s[0:1], 0, v[2:3]
	v_lshl_add_u64 v[18:19], s[12:13], 0, v[2:3]
	v_lshl_add_u64 v[22:23], s[14:15], 0, v[2:3]
	v_lshl_add_u64 v[66:67], s[16:17], 0, v[2:3]
	v_and_b32_e32 v84, 15, v82
	v_bfe_u32 v86, v82, 4, 2
	v_lshlrev_b32_e32 v3, 2, v82
	v_add_u32_e32 v95, 0x18000, v87
	v_lshl_add_u64 v[12:13], s[0:1], 0, v[0:1]
	v_lshl_add_u64 v[16:17], s[12:13], 0, v[0:1]
	v_lshl_add_u64 v[20:21], s[14:15], 0, v[0:1]
	v_lshl_add_u64 v[68:69], s[16:17], 0, v[0:1]
	v_lshlrev_b32_e32 v0, 6, v84
	v_lshlrev_b32_e32 v2, 4, v86
	v_and_b32_e32 v3, 32, v3
	s_mov_b64 s[12:13], 0x80
	v_readfirstlane_b32 s1, v95
	v_add_u32_e32 v96, 0x1a000, v87
	v_bitop3_b32 v24, v2, v3, v0 bitop3:0x36
	v_lshl_add_u64 v[2:3], v[12:13], 0, s[12:13]
	s_mov_b32 m0, s1
	v_readfirstlane_b32 s1, v96
	v_add_u32_e32 v97, 0x8000, v87
	s_waitcnt vmcnt(4)
	s_barrier
	global_load_lds_dwordx4 v[2:3], off
	v_lshl_add_u64 v[2:3], v[14:15], 0, s[12:13]
	s_mov_b32 m0, s1
	v_readfirstlane_b32 s1, v97
	v_add_u32_e32 v98, 0xa000, v87
	global_load_lds_dwordx4 v[2:3], off
	v_lshl_add_u64 v[2:3], v[16:17], 0, s[12:13]
	s_mov_b32 m0, s1
	v_readfirstlane_b32 s1, v98
	v_add_u32_e32 v100, 0x1c000, v87
	global_load_lds_dwordx4 v[2:3], off
	v_lshl_add_u64 v[2:3], v[18:19], 0, s[12:13]
	s_mov_b32 m0, s1
	v_readfirstlane_b32 s1, v100
	v_add_u32_e32 v101, 0x1e000, v87
	global_load_lds_dwordx4 v[2:3], off
	v_lshl_add_u64 v[2:3], v[20:21], 0, s[12:13]
	s_mov_b32 m0, s1
	v_readfirstlane_b32 s1, v101
	global_load_lds_dwordx4 v[2:3], off
	v_lshl_add_u64 v[2:3], v[22:23], 0, s[12:13]
	s_mov_b32 m0, s1
	s_sub_i32 s5, s56, s54
	global_load_lds_dwordx4 v[2:3], off
	s_sub_i32 s5, s5, s77
	s_sext_i32_i16 s5, s5
	s_lshl_b32 s1, s76, 10
	s_lshl_b32 s5, s5, 8
	s_and_b32 s0, s52, 0x80
	s_add_i32 s1, s1, s5
	s_or_b32 s0, s0, s1
	s_ashr_i32 s1, s0, 31
	s_lshl_b64 s[12:13], s[0:1], 12
	s_add_u32 s12, s57, s12
	v_readlane_b32 s36, v253, 33
	s_addc_u32 s13, s63, s13
	v_readlane_b32 s48, v253, 45
	v_readlane_b32 s49, v253, 46
	s_add_u32 s10, s48, s10
	v_lshlrev_b32_e32 v2, 14, v7
	s_addc_u32 s11, s49, s11
	s_addk_i32 s0, 0x80
	v_lshlrev_b32_e32 v0, 14, v4
	v_and_b32_e32 v2, 0x7fff8000, v2
	s_ashr_i32 s1, s0, 31
	v_and_b32_e32 v0, 0x7fff8000, v0
	v_lshl_add_u32 v2, v9, 11, v2
	s_lshl_b64 s[0:1], s[0:1], 12
	v_lshl_add_u32 v0, v5, 11, v0
	v_or_b32_e32 v2, v2, v10
	s_add_u32 s0, s57, s0
	v_bfe_u32 v85, v82, 6, 2
	v_mov_b32_e32 v4, 0
	v_mov_b32_e32 v5, 0
	v_mov_b32_e32 v7, 0
	v_mov_b32_e32 v9, 0
	v_mov_b32_e32 v10, 0
	v_mov_b32_e32 v12, 0
	v_mov_b32_e32 v13, 0
	v_mov_b32_e32 v14, 0
	v_mov_b32_e32 v15, 0
	v_mov_b32_e32 v16, 0
	v_mov_b32_e32 v17, 0
	v_mov_b32_e32 v18, 0
	v_mov_b32_e32 v19, 0
	v_mov_b32_e32 v20, 0
	v_mov_b32_e32 v21, 0
	v_mov_b32_e32 v22, 0
	v_mov_b32_e32 v23, 0
	v_mov_b32_e32 v27, 0
	v_mov_b32_e32 v28, 0
	v_mov_b32_e32 v29, 0
	v_mov_b32_e32 v34, 0
	v_mov_b32_e32 v35, 0
	v_mov_b32_e32 v36, 0
	v_mov_b32_e32 v37, 0
	v_mov_b32_e32 v38, 0
	v_mov_b32_e32 v39, 0
	v_mov_b32_e32 v40, 0
	v_mov_b32_e32 v41, 0
	v_mov_b32_e32 v42, 0
	v_mov_b32_e32 v43, 0
	v_mov_b32_e32 v44, 0
	v_mov_b32_e32 v45, 0
	v_mov_b32_e32 v46, 0
	v_mov_b32_e32 v47, 0
	v_mov_b32_e32 v48, 0
	v_mov_b32_e32 v49, 0
	v_mov_b32_e32 v50, 0
	v_mov_b32_e32 v51, 0
	v_mov_b32_e32 v52, 0
	v_mov_b32_e32 v53, 0
	v_mov_b32_e32 v54, 0
	v_mov_b32_e32 v55, 0
	v_mov_b32_e32 v56, 0
	v_mov_b32_e32 v57, 0
	v_mov_b32_e32 v58, 0
	v_mov_b32_e32 v59, 0
	v_mov_b32_e32 v60, 0
	v_mov_b32_e32 v61, 0
	v_mov_b32_e32 v62, 0
	v_mov_b32_e32 v63, 0
	v_mov_b32_e32 v64, 0
	v_mov_b32_e32 v65, 0
	v_mov_b32_e32 v30, 0
	v_mov_b32_e32 v31, 0
	v_mov_b32_e32 v32, 0
	v_mov_b32_e32 v33, 0
	s_waitcnt vmcnt(6)
	v_or_b32_e32 v0, v0, v6
	v_add_lshl_u32 v2, v2, v11, 1
	v_mov_b32_e32 v3, v1
	s_addc_u32 s1, s63, s1
	v_lshlrev_b32_e32 v25, 13, v83
	v_lshl_or_b32 v26, v85, 12, v212
	v_add_lshl_u32 v0, v0, v8, 1
	v_lshl_add_u64 v[72:73], s[12:13], 0, v[2:3]
	v_lshl_add_u64 v[76:77], s[10:11], 0, v[2:3]
	v_lshl_add_u64 v[80:81], s[0:1], 0, v[2:3]
	v_mov_b32_e32 v2, 0
	v_lshl_add_u64 v[70:71], s[12:13], 0, v[0:1]
	v_lshl_add_u64 v[74:75], s[10:11], 0, v[0:1]
	v_lshl_add_u64 v[78:79], s[0:1], 0, v[0:1]
	s_mov_b32 s0, -2
	s_mov_b64 s[10:11], 0
	v_add_u32_e32 v99, v26, v24
	v_add_u32_e32 v0, v25, v24
	v_mov_b32_e32 v3, v2
	v_mov_b32_e32 v6, v2
	v_mov_b32_e32 v8, v2
	v_mov_b32_e32 v11, v2
	v_mov_b32_e32 v24, v2
	v_mov_b32_e32 v25, v2
	v_mov_b32_e32 v26, v2
	s_barrier
	v_readlane_b32 s37, v253, 34
	v_readlane_b32 s38, v253, 35
	v_readlane_b32 s39, v253, 36
	v_readlane_b32 s40, v253, 37
	v_readlane_b32 s41, v253, 38
	v_readlane_b32 s42, v253, 39
	v_readlane_b32 s43, v253, 40
	v_readlane_b32 s44, v253, 41
	v_readlane_b32 s45, v253, 42
	v_readlane_b32 s46, v253, 43
	v_readlane_b32 s47, v253, 44
	v_readlane_b32 s50, v253, 47
	v_readlane_b32 s51, v253, 48
	v_add_u32_e32 v102, 0xc000, v87
	v_add_u32_e32 v103, 0xe000, v87
	v_readfirstlane_b32 s1, v87
	s_nop 1

.LBB0_179:
	s_or_b64 exec, exec, s[52:53]
	v_mov_b32_e32 v3, v1
	v_lshl_add_u64 v[14:15], s[0:1], 0, v[2:3]
	v_lshl_add_u64 v[18:19], s[16:17], 0, v[2:3]
	v_lshl_add_u64 v[22:23], s[72:73], 0, v[2:3]
	v_lshl_add_u64 v[130:131], s[76:77], 0, v[2:3]
	v_and_b32_e32 v146, 15, v142
	v_bfe_u32 v145, v142, 4, 2
	v_lshlrev_b32_e32 v3, 2, v142
	v_add_u32_e32 v156, 0x18000, v147
	v_lshl_add_u64 v[12:13], s[0:1], 0, v[0:1]
	v_lshl_add_u64 v[16:17], s[16:17], 0, v[0:1]
	v_lshl_add_u64 v[20:21], s[72:73], 0, v[0:1]
	v_lshl_add_u64 v[132:133], s[76:77], 0, v[0:1]
	v_lshlrev_b32_e32 v0, 6, v146
	v_lshlrev_b32_e32 v2, 4, v145
	v_and_b32_e32 v3, 32, v3
	s_mov_b64 s[16:17], 0x80
	v_readfirstlane_b32 s0, v156
	v_add_u32_e32 v157, 0x1a000, v147
	v_bitop3_b32 v24, v2, v3, v0 bitop3:0x36
	v_lshl_add_u64 v[2:3], v[12:13], 0, s[16:17]
	s_mov_b32 m0, s0
	v_readfirstlane_b32 s0, v157
	v_add_u32_e32 v158, 0x8000, v147
	s_waitcnt vmcnt(4)
	s_barrier
	global_load_lds_dwordx4 v[2:3], off
	v_lshl_add_u64 v[2:3], v[14:15], 0, s[16:17]
	s_mov_b32 m0, s0
	v_readfirstlane_b32 s0, v158
	v_add_u32_e32 v159, 0xa000, v147
	global_load_lds_dwordx4 v[2:3], off
	v_lshl_add_u64 v[2:3], v[16:17], 0, s[16:17]
	s_mov_b32 m0, s0
	v_readfirstlane_b32 s0, v159
	v_add_u32_e32 v160, 0x1c000, v147
	global_load_lds_dwordx4 v[2:3], off
	v_lshl_add_u64 v[2:3], v[18:19], 0, s[16:17]
	s_mov_b32 m0, s0
	v_readfirstlane_b32 s0, v160
	v_add_u32_e32 v161, 0x1e000, v147
	global_load_lds_dwordx4 v[2:3], off
	v_lshl_add_u64 v[2:3], v[20:21], 0, s[16:17]
	s_mov_b32 m0, s0
	v_readfirstlane_b32 s0, v161
	global_load_lds_dwordx4 v[2:3], off
	v_lshl_add_u64 v[2:3], v[22:23], 0, s[16:17]
	s_mov_b32 m0, s0
	v_lshlrev_b32_e32 v0, 14, v4
	global_load_lds_dwordx4 v[2:3], off
	v_lshlrev_b32_e32 v2, 14, v7
	v_and_b32_e32 v0, 0x7fff8000, v0
	v_and_b32_e32 v2, 0x7fff8000, v2
	v_lshl_add_u32 v0, v5, 11, v0
	v_lshl_add_u32 v2, v9, 11, v2
	v_or_b32_e32 v0, v0, v6
	s_add_u32 s0, s57, s12
	v_or_b32_e32 v2, v2, v10
	v_readlane_b32 s36, v253, 33
	v_add_lshl_u32 v0, v0, v8, 1
	s_addc_u32 s1, s63, s13
	v_add_lshl_u32 v2, v2, v11, 1
	v_mov_b32_e32 v3, v1
	v_readlane_b32 s48, v253, 45
	v_lshl_add_u64 v[134:135], s[0:1], 0, v[0:1]
	v_lshl_add_u64 v[136:137], s[0:1], 0, v[2:3]
	v_readlane_b32 s49, v253, 46
	s_add_u32 s0, s48, s14
	v_bfe_u32 v144, v142, 6, 2
	v_mov_b32_e32 v4, 0
	v_mov_b32_e32 v5, 0
	v_mov_b32_e32 v6, 0
	v_mov_b32_e32 v7, 0
	v_mov_b32_e32 v8, 0
	v_mov_b32_e32 v9, 0
	v_mov_b32_e32 v10, 0
	v_mov_b32_e32 v11, 0
	v_mov_b32_e32 v12, 0
	v_mov_b32_e32 v13, 0
	v_mov_b32_e32 v14, 0
	v_mov_b32_e32 v15, 0
	v_mov_b32_e32 v16, 0
	v_mov_b32_e32 v17, 0
	v_mov_b32_e32 v18, 0
	v_mov_b32_e32 v19, 0
	v_mov_b32_e32 v20, 0
	v_mov_b32_e32 v21, 0
	v_mov_b32_e32 v22, 0
	v_mov_b32_e32 v23, 0
	v_mov_b32_e32 v27, 0
	v_mov_b32_e32 v28, 0
	v_mov_b32_e32 v29, 0
	v_mov_b32_e32 v30, 0
	v_mov_b32_e32 v31, 0
	v_mov_b32_e32 v32, 0
	v_mov_b32_e32 v33, 0
	v_mov_b32_e32 v34, 0
	v_mov_b32_e32 v35, 0
	v_mov_b32_e32 v36, 0
	v_mov_b32_e32 v37, 0
	v_mov_b32_e32 v38, 0
	v_mov_b32_e32 v39, 0
	v_mov_b32_e32 v40, 0
	v_mov_b32_e32 v41, 0
	v_mov_b32_e32 v42, 0
	v_mov_b32_e32 v43, 0
	v_mov_b32_e32 v44, 0
	v_mov_b32_e32 v45, 0
	v_mov_b32_e32 v46, 0
	v_mov_b32_e32 v47, 0
	v_mov_b32_e32 v48, 0
	v_mov_b32_e32 v49, 0
	v_mov_b32_e32 v50, 0
	v_mov_b32_e32 v51, 0
	v_mov_b32_e32 v52, 0
	v_mov_b32_e32 v53, 0
	v_mov_b32_e32 v54, 0
	v_mov_b32_e32 v55, 0
	v_mov_b32_e32 v56, 0
	v_mov_b32_e32 v57, 0
	v_mov_b32_e32 v58, 0
	v_mov_b32_e32 v59, 0
	v_mov_b32_e32 v60, 0
	v_mov_b32_e32 v61, 0
	v_mov_b32_e32 v62, 0
	v_mov_b32_e32 v63, 0
	v_mov_b32_e32 v64, 0
	v_mov_b32_e32 v65, 0
	v_mov_b32_e32 v66, 0
	v_mov_b32_e32 v67, 0
	v_mov_b32_e32 v68, 0
	v_mov_b32_e32 v69, 0
	v_mov_b32_e32 v70, 0
	v_mov_b32_e32 v71, 0
	v_mov_b32_e32 v72, 0
	v_mov_b32_e32 v73, 0
	v_mov_b32_e32 v74, 0
	v_mov_b32_e32 v75, 0
	v_mov_b32_e32 v76, 0
	v_mov_b32_e32 v77, 0
	v_mov_b32_e32 v78, 0
	v_mov_b32_e32 v79, 0
	v_mov_b32_e32 v80, 0
	v_mov_b32_e32 v81, 0
	v_mov_b32_e32 v82, 0
	v_mov_b32_e32 v83, 0
	v_mov_b32_e32 v84, 0
	v_mov_b32_e32 v85, 0
	v_mov_b32_e32 v86, 0
	v_mov_b32_e32 v87, 0
	v_mov_b32_e32 v88, 0
	v_mov_b32_e32 v89, 0
	v_mov_b32_e32 v90, 0
	v_mov_b32_e32 v91, 0
	v_mov_b32_e32 v92, 0
	v_mov_b32_e32 v93, 0
	v_mov_b32_e32 v94, 0
	v_mov_b32_e32 v95, 0
	v_mov_b32_e32 v96, 0
	v_mov_b32_e32 v97, 0
	v_mov_b32_e32 v98, 0
	v_mov_b32_e32 v99, 0
	v_mov_b32_e32 v100, 0
	v_mov_b32_e32 v101, 0
	v_mov_b32_e32 v102, 0
	v_mov_b32_e32 v103, 0
	v_mov_b32_e32 v104, 0
	v_mov_b32_e32 v105, 0
	v_mov_b32_e32 v106, 0
	v_mov_b32_e32 v107, 0
	v_mov_b32_e32 v108, 0
	v_mov_b32_e32 v109, 0
	v_mov_b32_e32 v110, 0
	v_mov_b32_e32 v111, 0
	v_mov_b32_e32 v112, 0
	v_mov_b32_e32 v113, 0
	v_mov_b32_e32 v114, 0
	v_mov_b32_e32 v115, 0
	v_mov_b32_e32 v116, 0
	v_mov_b32_e32 v117, 0
	v_mov_b32_e32 v118, 0
	v_mov_b32_e32 v119, 0
	v_mov_b32_e32 v120, 0
	v_mov_b32_e32 v121, 0
	v_mov_b32_e32 v122, 0
	v_mov_b32_e32 v123, 0
	v_mov_b32_e32 v124, 0
	v_mov_b32_e32 v125, 0
	v_mov_b32_e32 v126, 0
	v_mov_b32_e32 v127, 0
	v_mov_b32_e32 v128, 0
	v_mov_b32_e32 v129, 0
	s_waitcnt vmcnt(6)
	s_addc_u32 s1, s49, s15
	v_lshlrev_b32_e32 v25, 13, v143
	v_lshl_or_b32 v26, v144, 12, v212
	v_lshl_add_u64 v[140:141], s[0:1], 0, v[2:3]
	v_mov_b32_e32 v2, 0
	v_lshl_add_u64 v[138:139], s[0:1], 0, v[0:1]
	s_mov_b32 s0, -2
	s_mov_b64 s[12:13], 0
	v_add_u32_e32 v151, v26, v24
	v_add_u32_e32 v0, v25, v24
	v_mov_b32_e32 v3, v2
	v_mov_b32_e32 v24, v2
	v_mov_b32_e32 v25, v2
	v_mov_b32_e32 v26, v2
	s_barrier
	v_readlane_b32 s37, v253, 34
	v_readlane_b32 s38, v253, 35
	v_readlane_b32 s39, v253, 36
	v_readlane_b32 s40, v253, 37
	v_readlane_b32 s41, v253, 38
	v_readlane_b32 s42, v253, 39
	v_readlane_b32 s43, v253, 40
	v_readlane_b32 s44, v253, 41
	v_readlane_b32 s45, v253, 42
	v_readlane_b32 s46, v253, 43
	v_readlane_b32 s47, v253, 44
	v_readlane_b32 s50, v253, 47
	v_readlane_b32 s51, v253, 48
	v_add_u32_e32 v162, 0xc000, v147
	v_add_u32_e32 v163, 0xe000, v147
	v_readfirstlane_b32 s1, v147
	s_nop 1

.LBB0_677:
	s_or_b64 exec, exec, s[16:17]
	v_mov_b32_e32 v3, v1
	v_lshl_add_u64 v[12:13], s[0:1], 0, v[2:3]
	v_lshl_add_u64 v[16:17], s[10:11], 0, v[2:3]
	v_lshl_add_u64 v[20:21], s[12:13], 0, v[2:3]
	v_lshl_add_u64 v[130:131], s[14:15], 0, v[2:3]
	v_and_b32_e32 v146, 15, v142
	v_bfe_u32 v145, v142, 4, 2
	v_lshlrev_b32_e32 v3, 2, v142
	v_add_u32_e32 v156, 0x18000, v147
	v_lshl_add_u64 v[10:11], s[0:1], 0, v[0:1]
	v_lshl_add_u64 v[14:15], s[10:11], 0, v[0:1]
	v_lshl_add_u64 v[18:19], s[12:13], 0, v[0:1]
	v_lshl_add_u64 v[132:133], s[14:15], 0, v[0:1]
	v_lshlrev_b32_e32 v0, 6, v146
	v_lshlrev_b32_e32 v2, 4, v145
	v_and_b32_e32 v3, 32, v3
	s_mov_b64 s[10:11], 0x80
	v_readfirstlane_b32 s0, v156
	v_add_u32_e32 v157, 0x1a000, v147
	v_bitop3_b32 v22, v2, v3, v0 bitop3:0x36
	v_lshl_add_u64 v[2:3], v[10:11], 0, s[10:11]
	s_mov_b32 m0, s0
	v_readfirstlane_b32 s0, v157
	v_add_u32_e32 v158, 0x8000, v147
	s_waitcnt vmcnt(4)
	s_barrier
	global_load_lds_dwordx4 v[2:3], off
	v_lshl_add_u64 v[2:3], v[12:13], 0, s[10:11]
	s_mov_b32 m0, s0
	v_readfirstlane_b32 s0, v158
	v_add_u32_e32 v159, 0xa000, v147
	global_load_lds_dwordx4 v[2:3], off
	v_lshl_add_u64 v[2:3], v[14:15], 0, s[10:11]
	s_mov_b32 m0, s0
	v_readfirstlane_b32 s0, v159
	v_add_u32_e32 v160, 0x1c000, v147
	global_load_lds_dwordx4 v[2:3], off
	v_lshl_add_u64 v[2:3], v[16:17], 0, s[10:11]
	s_mov_b32 m0, s0
	v_readfirstlane_b32 s0, v160
	v_add_u32_e32 v161, 0x1e000, v147
	global_load_lds_dwordx4 v[2:3], off
	v_lshl_add_u64 v[2:3], v[18:19], 0, s[10:11]
	s_mov_b32 m0, s0
	v_readfirstlane_b32 s0, v161
	global_load_lds_dwordx4 v[2:3], off
	v_lshl_add_u64 v[2:3], v[20:21], 0, s[10:11]
	s_mov_b32 m0, s0
	s_sub_i32 s1, s57, s64
	global_load_lds_dwordx4 v[2:3], off
	s_sub_i32 s1, s1, s63
	v_lshlrev_b32_e32 v0, 15, v4
	s_sext_i32_i16 s1, s1
	v_and_b32_e32 v0, 0xffff0000, v0
	s_lshl_b32 s0, s62, 10
	s_lshl_b32 s1, s1, 8
	v_lshl_add_u32 v0, v5, 12, v0
	v_and_b32_e32 v2, 1, v4
	s_add_i32 s0, s0, s1
	v_lshl_or_b32 v0, v2, 6, v0
	v_lshlrev_b32_e32 v2, 15, v6
	s_ashr_i32 s1, s0, 31
	v_and_b32_e32 v2, 0xffff0000, v2
	s_lshl_b64 s[0:1], s[0:1], 12
	v_lshl_add_u32 v2, v8, 12, v2
	v_and_b32_e32 v3, 1, v6
	s_add_u32 s0, s52, s0
	v_lshl_or_b32 v2, v3, 6, v2
	v_lshl_add_u32 v0, v7, 1, v0
	s_addc_u32 s1, s53, s1
	v_lshl_add_u32 v2, v9, 1, v2
	v_mov_b32_e32 v3, v1
	v_lshl_add_u64 v[134:135], s[0:1], 0, v[0:1]
	v_lshl_add_u64 v[136:137], s[0:1], 0, v[2:3]
	s_add_u32 s0, s88, s8
	v_bfe_u32 v144, v142, 6, 2
	v_mov_b32_e32 v4, 0
	v_mov_b32_e32 v5, 0
	v_mov_b32_e32 v6, 0
	v_mov_b32_e32 v7, 0
	v_mov_b32_e32 v8, 0
	v_mov_b32_e32 v9, 0
	v_mov_b32_e32 v10, 0
	v_mov_b32_e32 v11, 0
	v_mov_b32_e32 v12, 0
	v_mov_b32_e32 v13, 0
	v_mov_b32_e32 v14, 0
	v_mov_b32_e32 v15, 0
	v_mov_b32_e32 v16, 0
	v_mov_b32_e32 v17, 0
	v_mov_b32_e32 v18, 0
	v_mov_b32_e32 v19, 0
	v_mov_b32_e32 v20, 0
	v_mov_b32_e32 v21, 0
	v_mov_b32_e32 v25, 0
	v_mov_b32_e32 v26, 0
	v_mov_b32_e32 v27, 0
	v_mov_b32_e32 v28, 0
	v_mov_b32_e32 v29, 0
	v_mov_b32_e32 v30, 0
	v_mov_b32_e32 v31, 0
	v_mov_b32_e32 v32, 0
	v_mov_b32_e32 v33, 0
	v_mov_b32_e32 v34, 0
	v_mov_b32_e32 v35, 0
	v_mov_b32_e32 v36, 0
	v_mov_b32_e32 v37, 0
	v_mov_b32_e32 v38, 0
	v_mov_b32_e32 v39, 0
	v_mov_b32_e32 v40, 0
	v_mov_b32_e32 v41, 0
	v_mov_b32_e32 v42, 0
	v_mov_b32_e32 v43, 0
	v_mov_b32_e32 v44, 0
	v_mov_b32_e32 v45, 0
	v_mov_b32_e32 v46, 0
	v_mov_b32_e32 v47, 0
	v_mov_b32_e32 v48, 0
	v_mov_b32_e32 v49, 0
	v_mov_b32_e32 v50, 0
	v_mov_b32_e32 v51, 0
	v_mov_b32_e32 v52, 0
	v_mov_b32_e32 v53, 0
	v_mov_b32_e32 v54, 0
	v_mov_b32_e32 v55, 0
	v_mov_b32_e32 v56, 0
	v_mov_b32_e32 v57, 0
	v_mov_b32_e32 v58, 0
	v_mov_b32_e32 v59, 0
	v_mov_b32_e32 v60, 0
	v_mov_b32_e32 v61, 0
	v_mov_b32_e32 v62, 0
	v_mov_b32_e32 v63, 0
	v_mov_b32_e32 v64, 0
	v_mov_b32_e32 v65, 0
	v_mov_b32_e32 v66, 0
	v_mov_b32_e32 v67, 0
	v_mov_b32_e32 v68, 0
	v_mov_b32_e32 v69, 0
	v_mov_b32_e32 v70, 0
	v_mov_b32_e32 v71, 0
	v_mov_b32_e32 v72, 0
	v_mov_b32_e32 v73, 0
	v_mov_b32_e32 v74, 0
	v_mov_b32_e32 v75, 0
	v_mov_b32_e32 v76, 0
	v_mov_b32_e32 v77, 0
	v_mov_b32_e32 v78, 0
	v_mov_b32_e32 v79, 0
	v_mov_b32_e32 v80, 0
	v_mov_b32_e32 v81, 0
	v_mov_b32_e32 v82, 0
	v_mov_b32_e32 v83, 0
	v_mov_b32_e32 v84, 0
	v_mov_b32_e32 v85, 0
	v_mov_b32_e32 v86, 0
	v_mov_b32_e32 v87, 0
	v_mov_b32_e32 v88, 0
	v_mov_b32_e32 v89, 0
	v_mov_b32_e32 v90, 0
	v_mov_b32_e32 v91, 0
	v_mov_b32_e32 v92, 0
	v_mov_b32_e32 v93, 0
	v_mov_b32_e32 v94, 0
	v_mov_b32_e32 v95, 0
	v_mov_b32_e32 v96, 0
	v_mov_b32_e32 v97, 0
	v_mov_b32_e32 v98, 0
	v_mov_b32_e32 v99, 0
	v_mov_b32_e32 v100, 0
	v_mov_b32_e32 v101, 0
	v_mov_b32_e32 v102, 0
	v_mov_b32_e32 v103, 0
	v_mov_b32_e32 v104, 0
	v_mov_b32_e32 v105, 0
	v_mov_b32_e32 v106, 0
	v_mov_b32_e32 v107, 0
	v_mov_b32_e32 v108, 0
	v_mov_b32_e32 v109, 0
	v_mov_b32_e32 v110, 0
	v_mov_b32_e32 v111, 0
	v_mov_b32_e32 v112, 0
	v_mov_b32_e32 v113, 0
	v_mov_b32_e32 v114, 0
	v_mov_b32_e32 v115, 0
	v_mov_b32_e32 v116, 0
	v_mov_b32_e32 v117, 0
	v_mov_b32_e32 v118, 0
	v_mov_b32_e32 v119, 0
	v_mov_b32_e32 v120, 0
	v_mov_b32_e32 v121, 0
	v_mov_b32_e32 v122, 0
	v_mov_b32_e32 v123, 0
	v_mov_b32_e32 v124, 0
	v_mov_b32_e32 v125, 0
	v_mov_b32_e32 v126, 0
	v_mov_b32_e32 v127, 0
	v_mov_b32_e32 v128, 0
	v_mov_b32_e32 v129, 0
	s_waitcnt vmcnt(6)
	s_addc_u32 s1, s89, s9
	v_lshlrev_b32_e32 v23, 13, v143
	v_lshl_or_b32 v24, v144, 12, v212
	v_lshl_add_u64 v[140:141], s[0:1], 0, v[2:3]
	v_mov_b32_e32 v2, 0
	v_lshl_add_u64 v[138:139], s[0:1], 0, v[0:1]
	s_mov_b32 s0, -2
	s_mov_b64 s[8:9], 0
	v_add_u32_e32 v151, v24, v22
	v_add_u32_e32 v0, v23, v22
	v_mov_b32_e32 v3, v2
	v_mov_b32_e32 v22, v2
	v_mov_b32_e32 v23, v2
	v_mov_b32_e32 v24, v2
	s_barrier
	v_add_u32_e32 v162, 0xc000, v147
	v_add_u32_e32 v163, 0xe000, v147
	v_readfirstlane_b32 s1, v147
	s_nop 1

.LBB0_688:
	s_or_b64 exec, exec, s[14:15]
	v_mov_b32_e32 v67, v1
	v_add_u32_e32 v94, 0x18000, v85
	v_lshl_add_u64 v[10:11], s[0:1], 0, v[0:1]
	v_lshl_add_u64 v[12:13], s[0:1], 0, v[66:67]
	v_lshl_add_u64 v[14:15], s[10:11], 0, v[0:1]
	v_lshl_add_u64 v[16:17], s[10:11], 0, v[66:67]
	s_mov_b64 s[10:11], 0x80
	v_readfirstlane_b32 s1, v94
	v_add_u32_e32 v96, 0x1a000, v85
	v_lshl_add_u64 v[10:11], v[10:11], 0, s[10:11]
	s_mov_b32 m0, s1
	v_readfirstlane_b32 s1, v96
	v_add_u32_e32 v97, 0x8000, v85
	s_waitcnt vmcnt(4)
	s_barrier
	global_load_lds_dwordx4 v[10:11], off
	v_lshl_add_u64 v[10:11], v[12:13], 0, s[10:11]
	s_mov_b32 m0, s1
	v_readfirstlane_b32 s1, v97
	v_add_u32_e32 v98, 0xa000, v85
	global_load_lds_dwordx4 v[10:11], off
	v_lshl_add_u64 v[10:11], v[14:15], 0, s[10:11]
	s_mov_b32 m0, s1
	v_readfirstlane_b32 s1, v98
	v_add_u32_e32 v99, 0x1c000, v85
	v_lshl_add_u64 v[18:19], s[12:13], 0, v[0:1]
	global_load_lds_dwordx4 v[10:11], off
	v_lshl_add_u64 v[10:11], v[16:17], 0, s[10:11]
	s_mov_b32 m0, s1
	v_readfirstlane_b32 s1, v99
	v_add_u32_e32 v100, 0x1e000, v85
	v_lshl_add_u64 v[20:21], s[12:13], 0, v[66:67]
	global_load_lds_dwordx4 v[10:11], off
	v_lshl_add_u64 v[10:11], v[18:19], 0, s[10:11]
	s_mov_b32 m0, s1
	v_readfirstlane_b32 s1, v100
	global_load_lds_dwordx4 v[10:11], off
	v_lshl_add_u64 v[10:11], v[20:21], 0, s[10:11]
	s_mov_b32 m0, s1
	s_sub_i32 s10, s62, s54
	global_load_lds_dwordx4 v[10:11], off
	s_sub_i32 s10, s10, s64
	s_sext_i32_i16 s10, s10
	s_lshl_b32 s1, s63, 10
	s_lshl_b32 s10, s10, 8
	s_movk_i32 s14, 0x1600
	s_and_b32 s0, s52, 0x80
	s_add_i32 s1, s1, s10
	v_lshrrev_b32_e32 v10, 1, v2
	v_mul_lo_u32 v2, v4, s14
	s_mov_b32 s11, 0x16000
	s_or_b32 s12, s0, s1
	v_mad_u64_u32 v[10:11], s[0:1], v10, s11, v[2:3]
	s_mul_i32 s13, s12, 0x2c00
	v_or_b32_e32 v2, v10, v3
	s_mul_hi_i32 s10, s12, 0x2c00
	v_add_lshl_u32 v2, v2, v5, 1
	s_add_u32 s0, s16, s13
	v_lshrrev_b32_e32 v5, 1, v6
	v_mul_lo_u32 v4, v8, s14
	s_addc_u32 s1, s17, s10
	v_mad_u64_u32 v[4:5], s[10:11], v5, s11, v[4:5]
	v_or_b32_e32 v4, v4, v7
	v_mov_b32_e32 v3, v1
	v_add_lshl_u32 v4, v4, v9, 1
	v_mov_b32_e32 v5, v1
	v_lshl_add_u64 v[68:69], s[0:1], 0, v[2:3]
	v_lshl_add_u64 v[70:71], s[0:1], 0, v[4:5]
	s_add_u32 s0, s20, s66
	s_addc_u32 s1, s21, s72
	s_addk_i32 s12, 0x80
	s_add_i32 s13, s13, 0x160000
	v_and_b32_e32 v84, 15, v80
	v_bfe_u32 v83, v80, 4, 2
	v_lshlrev_b32_e32 v24, 2, v80
	v_lshl_add_u64 v[72:73], s[0:1], 0, v[2:3]
	v_lshl_add_u64 v[74:75], s[0:1], 0, v[4:5]
	s_mul_hi_i32 s1, s12, 0x2c00
	s_add_u32 s0, s16, s13
	v_bfe_u32 v82, v80, 6, 2
	v_lshlrev_b32_e32 v22, 6, v84
	v_lshlrev_b32_e32 v23, 4, v83
	v_and_b32_e32 v24, 32, v24
	v_mov_b32_e32 v6, 0
	v_mov_b32_e32 v7, 0
	v_mov_b32_e32 v8, 0
	v_mov_b32_e32 v9, 0
	v_mov_b32_e32 v10, 0
	v_mov_b32_e32 v11, 0
	v_mov_b32_e32 v12, 0
	v_mov_b32_e32 v13, 0
	v_mov_b32_e32 v14, 0
	v_mov_b32_e32 v15, 0
	v_mov_b32_e32 v16, 0
	v_mov_b32_e32 v17, 0
	v_mov_b32_e32 v18, 0
	v_mov_b32_e32 v19, 0
	v_mov_b32_e32 v20, 0
	v_mov_b32_e32 v21, 0
	v_mov_b32_e32 v25, 0
	v_mov_b32_e32 v26, 0
	v_mov_b32_e32 v27, 0
	v_mov_b32_e32 v28, 0
	v_mov_b32_e32 v29, 0
	v_mov_b32_e32 v34, 0
	v_mov_b32_e32 v35, 0
	v_mov_b32_e32 v36, 0
	v_mov_b32_e32 v37, 0
	v_mov_b32_e32 v38, 0
	v_mov_b32_e32 v39, 0
	v_mov_b32_e32 v40, 0
	v_mov_b32_e32 v41, 0
	v_mov_b32_e32 v42, 0
	v_mov_b32_e32 v43, 0
	v_mov_b32_e32 v44, 0
	v_mov_b32_e32 v45, 0
	v_mov_b32_e32 v46, 0
	v_mov_b32_e32 v47, 0
	v_mov_b32_e32 v48, 0
	v_mov_b32_e32 v49, 0
	v_mov_b32_e32 v50, 0
	v_mov_b32_e32 v51, 0
	v_mov_b32_e32 v52, 0
	v_mov_b32_e32 v53, 0
	v_mov_b32_e32 v54, 0
	v_mov_b32_e32 v55, 0
	v_mov_b32_e32 v56, 0
	v_mov_b32_e32 v57, 0
	v_mov_b32_e32 v58, 0
	v_mov_b32_e32 v59, 0
	v_mov_b32_e32 v60, 0
	v_mov_b32_e32 v61, 0
	v_mov_b32_e32 v62, 0
	v_mov_b32_e32 v63, 0
	v_mov_b32_e32 v64, 0
	v_mov_b32_e32 v65, 0
	v_mov_b32_e32 v30, 0
	v_mov_b32_e32 v31, 0
	v_mov_b32_e32 v32, 0
	v_mov_b32_e32 v33, 0
	s_waitcnt vmcnt(6)
	s_addc_u32 s1, s17, s1
	v_bitop3_b32 v22, v23, v24, v22 bitop3:0x36
	v_lshlrev_b32_e32 v23, 13, v81
	v_lshl_or_b32 v24, v82, 12, v212
	v_lshl_add_u64 v[76:77], s[0:1], 0, v[2:3]
	v_mov_b32_e32 v2, 0
	v_lshl_add_u64 v[78:79], s[0:1], 0, v[4:5]
	s_mov_b32 s0, -2
	s_mov_b64 s[10:11], 0
	v_add_u32_e32 v95, v24, v22
	v_add_u32_e32 v93, v23, v22
	v_mov_b32_e32 v3, v2
	v_mov_b32_e32 v4, v2
	v_mov_b32_e32 v5, v2
	v_mov_b32_e32 v22, v2
	v_mov_b32_e32 v23, v2
	v_mov_b32_e32 v24, v2
	s_barrier
	v_add_u32_e32 v101, 0xc000, v85
	v_add_u32_e32 v102, 0xe000, v85
	v_readfirstlane_b32 s1, v85
	s_nop 1

.LBB0_760:
	s_or_b64 exec, exec, s[14:15]
	v_mov_b32_e32 v131, v1
	v_add_u32_e32 v155, 0x18000, v145
	v_lshl_add_u64 v[10:11], s[0:1], 0, v[0:1]
	v_lshl_add_u64 v[12:13], s[0:1], 0, v[130:131]
	v_lshl_add_u64 v[18:19], s[12:13], 0, v[0:1]
	v_lshl_add_u64 v[20:21], s[12:13], 0, v[130:131]
	s_mov_b64 s[12:13], 0x80
	v_readfirstlane_b32 s0, v155
	v_add_u32_e32 v156, 0x1a000, v145
	v_lshl_add_u64 v[10:11], v[10:11], 0, s[12:13]
	s_mov_b32 m0, s0
	v_readfirstlane_b32 s0, v156
	v_add_u32_e32 v157, 0x8000, v145
	v_lshl_add_u64 v[14:15], s[8:9], 0, v[0:1]
	s_waitcnt vmcnt(4)
	s_barrier
	global_load_lds_dwordx4 v[10:11], off
	v_lshl_add_u64 v[10:11], v[12:13], 0, s[12:13]
	s_mov_b32 m0, s0
	v_readfirstlane_b32 s0, v157
	v_add_u32_e32 v158, 0xa000, v145
	v_lshl_add_u64 v[16:17], s[8:9], 0, v[130:131]
	global_load_lds_dwordx4 v[10:11], off
	v_lshl_add_u64 v[10:11], v[14:15], 0, s[12:13]
	s_mov_b32 m0, s0
	v_readfirstlane_b32 s0, v158
	v_add_u32_e32 v159, 0x1c000, v145
	global_load_lds_dwordx4 v[10:11], off
	v_lshl_add_u64 v[10:11], v[16:17], 0, s[12:13]
	s_mov_b32 m0, s0
	v_readfirstlane_b32 s0, v159
	v_add_u32_e32 v160, 0x1e000, v145
	global_load_lds_dwordx4 v[10:11], off
	v_lshl_add_u64 v[10:11], v[18:19], 0, s[12:13]
	s_mov_b32 m0, s0
	v_readfirstlane_b32 s0, v160
	global_load_lds_dwordx4 v[10:11], off
	v_lshl_add_u64 v[10:11], v[20:21], 0, s[12:13]
	s_mov_b32 m0, s0
	s_movk_i32 s13, 0x1600
	global_load_lds_dwordx4 v[10:11], off
	v_lshrrev_b32_e32 v10, 1, v2
	v_mul_lo_u32 v2, v4, s13
	s_mov_b32 s12, 0x16000
	v_mad_u64_u32 v[10:11], s[0:1], v10, s12, v[2:3]
	v_or_b32_e32 v2, v10, v3
	v_add_lshl_u32 v2, v2, v5, 1
	v_lshrrev_b32_e32 v5, 1, v6
	v_mul_lo_u32 v4, v8, s13
	v_mad_u64_u32 v[4:5], s[12:13], v5, s12, v[4:5]
	s_add_u32 s0, s16, s57
	v_or_b32_e32 v4, v4, v7
	v_mov_b32_e32 v3, v1
	s_addc_u32 s1, s17, s54
	v_add_lshl_u32 v4, v4, v9, 1
	v_mov_b32_e32 v5, v1
	v_and_b32_e32 v144, 15, v140
	v_bfe_u32 v143, v140, 4, 2
	v_lshlrev_b32_e32 v24, 2, v140
	v_lshl_add_u64 v[132:133], s[0:1], 0, v[2:3]
	v_lshl_add_u64 v[134:135], s[0:1], 0, v[4:5]
	s_add_u32 s0, s20, s10
	v_bfe_u32 v142, v140, 6, 2
	v_lshlrev_b32_e32 v22, 6, v144
	v_lshlrev_b32_e32 v23, 4, v143
	v_and_b32_e32 v24, 32, v24
	v_mov_b32_e32 v6, 0
	v_mov_b32_e32 v7, 0
	v_mov_b32_e32 v8, 0
	v_mov_b32_e32 v9, 0
	v_mov_b32_e32 v10, 0
	v_mov_b32_e32 v11, 0
	v_mov_b32_e32 v12, 0
	v_mov_b32_e32 v13, 0
	v_mov_b32_e32 v14, 0
	v_mov_b32_e32 v15, 0
	v_mov_b32_e32 v16, 0
	v_mov_b32_e32 v17, 0
	v_mov_b32_e32 v18, 0
	v_mov_b32_e32 v19, 0
	v_mov_b32_e32 v20, 0
	v_mov_b32_e32 v21, 0
	v_mov_b32_e32 v25, 0
	v_mov_b32_e32 v26, 0
	v_mov_b32_e32 v27, 0
	v_mov_b32_e32 v28, 0
	v_mov_b32_e32 v29, 0
	v_mov_b32_e32 v30, 0
	v_mov_b32_e32 v31, 0
	v_mov_b32_e32 v32, 0
	v_mov_b32_e32 v33, 0
	v_mov_b32_e32 v34, 0
	v_mov_b32_e32 v35, 0
	v_mov_b32_e32 v36, 0
	v_mov_b32_e32 v37, 0
	v_mov_b32_e32 v38, 0
	v_mov_b32_e32 v39, 0
	v_mov_b32_e32 v40, 0
	v_mov_b32_e32 v41, 0
	v_mov_b32_e32 v42, 0
	v_mov_b32_e32 v43, 0
	v_mov_b32_e32 v44, 0
	v_mov_b32_e32 v45, 0
	v_mov_b32_e32 v46, 0
	v_mov_b32_e32 v47, 0
	v_mov_b32_e32 v48, 0
	v_mov_b32_e32 v49, 0
	v_mov_b32_e32 v50, 0
	v_mov_b32_e32 v51, 0
	v_mov_b32_e32 v52, 0
	v_mov_b32_e32 v53, 0
	v_mov_b32_e32 v54, 0
	v_mov_b32_e32 v55, 0
	v_mov_b32_e32 v56, 0
	v_mov_b32_e32 v57, 0
	v_mov_b32_e32 v58, 0
	v_mov_b32_e32 v59, 0
	v_mov_b32_e32 v60, 0
	v_mov_b32_e32 v61, 0
	v_mov_b32_e32 v62, 0
	v_mov_b32_e32 v63, 0
	v_mov_b32_e32 v64, 0
	v_mov_b32_e32 v65, 0
	v_mov_b32_e32 v66, 0
	v_mov_b32_e32 v67, 0
	v_mov_b32_e32 v68, 0
	v_mov_b32_e32 v69, 0
	v_mov_b32_e32 v70, 0
	v_mov_b32_e32 v71, 0
	v_mov_b32_e32 v72, 0
	v_mov_b32_e32 v73, 0
	v_mov_b32_e32 v74, 0
	v_mov_b32_e32 v75, 0
	v_mov_b32_e32 v76, 0
	v_mov_b32_e32 v77, 0
	v_mov_b32_e32 v78, 0
	v_mov_b32_e32 v79, 0
	v_mov_b32_e32 v80, 0
	v_mov_b32_e32 v81, 0
	v_mov_b32_e32 v82, 0
	v_mov_b32_e32 v83, 0
	v_mov_b32_e32 v84, 0
	v_mov_b32_e32 v85, 0
	v_mov_b32_e32 v86, 0
	v_mov_b32_e32 v87, 0
	v_mov_b32_e32 v88, 0
	v_mov_b32_e32 v89, 0
	v_mov_b32_e32 v90, 0
	v_mov_b32_e32 v91, 0
	v_mov_b32_e32 v92, 0
	v_mov_b32_e32 v93, 0
	v_mov_b32_e32 v94, 0
	v_mov_b32_e32 v95, 0
	v_mov_b32_e32 v96, 0
	v_mov_b32_e32 v97, 0
	v_mov_b32_e32 v98, 0
	v_mov_b32_e32 v99, 0
	v_mov_b32_e32 v100, 0
	v_mov_b32_e32 v101, 0
	v_mov_b32_e32 v102, 0
	v_mov_b32_e32 v103, 0
	v_mov_b32_e32 v104, 0
	v_mov_b32_e32 v105, 0
	v_mov_b32_e32 v106, 0
	v_mov_b32_e32 v107, 0
	v_mov_b32_e32 v108, 0
	v_mov_b32_e32 v109, 0
	v_mov_b32_e32 v110, 0
	v_mov_b32_e32 v111, 0
	v_mov_b32_e32 v112, 0
	v_mov_b32_e32 v113, 0
	v_mov_b32_e32 v114, 0
	v_mov_b32_e32 v115, 0
	v_mov_b32_e32 v116, 0
	v_mov_b32_e32 v117, 0
	v_mov_b32_e32 v118, 0
	v_mov_b32_e32 v119, 0
	v_mov_b32_e32 v120, 0
	v_mov_b32_e32 v121, 0
	v_mov_b32_e32 v122, 0
	v_mov_b32_e32 v123, 0
	v_mov_b32_e32 v124, 0
	v_mov_b32_e32 v125, 0
	v_mov_b32_e32 v126, 0
	v_mov_b32_e32 v127, 0
	v_mov_b32_e32 v128, 0
	v_mov_b32_e32 v129, 0
	s_waitcnt vmcnt(6)
	s_addc_u32 s1, s21, s11
	v_bitop3_b32 v22, v23, v24, v22 bitop3:0x36
	v_lshlrev_b32_e32 v23, 13, v141
	v_lshl_or_b32 v24, v142, 12, v212
	v_lshl_add_u64 v[136:137], s[0:1], 0, v[2:3]
	v_mov_b32_e32 v2, 0
	v_lshl_add_u64 v[138:139], s[0:1], 0, v[4:5]
	s_mov_b32 s0, -2
	s_mov_b64 s[10:11], 0
	v_add_u32_e32 v148, v24, v22
	v_add_u32_e32 v147, v23, v22
	v_mov_b32_e32 v3, v2
	v_mov_b32_e32 v4, v2
	v_mov_b32_e32 v5, v2
	v_mov_b32_e32 v22, v2
	v_mov_b32_e32 v23, v2
	v_mov_b32_e32 v24, v2
	s_barrier
	v_add_u32_e32 v161, 0xc000, v145
	v_add_u32_e32 v162, 0xe000, v145
	v_readfirstlane_b32 s1, v145
	s_nop 1
